# GEMM2 K-loop: readiness counters also read one iteration early; the last-iteration poll and its pipeline drain are skipped when that snapshot is already complete
# baseline (speedup 1.0000x reference)
.LBB0_1085:
	s_cmp_eq_u32 s89, 12
	s_cbranch_scc0 .Lxp_nosnap
	global_load_dword v250, v149, s[46:47] sc1
	global_load_dword v251, v149, s[48:49] sc1
.Lxp_nosnap:
	s_cmp_eq_u32 s89, 14
	s_cselect_b64 s[60:61], -1, 0
	s_and_b64 s[58:59], s[42:43], s[60:61]
	s_andn2_b64 vcc, exec, s[58:59]
	s_cbranch_vccnz .LBB0_1099
	s_and_b64 vcc, exec, s[86:87]
	s_cbranch_vccnz .LBB0_1098
	v_cmp_le_u32_e32 vcc, 12, v250
	v_cmp_le_u32_e64 s[62:63], 3, v251
	s_and_b64 vcc, vcc, s[62:63]
	s_cbranch_vccz .Lxp_poll
	s_barrier
	s_branch .LBB0_1099
.Lxp_poll:
	v_mbcnt_lo_u32_b32 v154, -1, 0
	v_mbcnt_hi_u32_b32 v154, -1, v154
	s_nop 0
	v_cmp_eq_u32_e32 vcc, 0, v154
	s_and_saveexec_b64 s[58:59], vcc
	s_cbranch_execz .LBB0_1097
	s_mov_b32 s90, 0xfffff
	s_branch .LBB0_1090
